# FFN-in x4 unit scheduler: the two generic integer divisions (v_rcp_iflag + readfirstlane chains, ~100 instr per unit) replaced by the shift/mask form valid for these panel counts
# baseline (speedup 1.0000x reference)
;     __host__ __device__ bool next(int i, Unit& u) const {
;         const long L = (long)i * G + c; if (L >= nwg) return false;
;     ...
;         int nN = this->nN, nM = this->nM, nwg = this->nwg; asm volatile("" : "+s"(nN), "+s"(nM), "+s"(nwg));
;     ...
;         int wgid = (int)L; { const int q = nwg / NXCD, r = nwg % NXCD, xcd = wgid % NXCD, off = wgid / NXCD; wgid = (xcd < r ? xcd * (q + 1) : r * (q + 1) + (xcd - r) * q) + off; }
;         const int nig = wgm * nN, gid = wgid / nig, fm = gid * wgm, gsz = (nM - fm) < wgm ? (nM - fm) : wgm;
;         u.pm = fm + ((wgid % nig) % gsz); u.pn = (wgid % nig) / gsz; u.z = 0; u.k0 = 0; u.nt = ntk;
;         if (latonly) u.pm += 1 + (u.pm >= 32 ? 1 : 0);
.LBB0_293:
	s_add_i32 s10, s10, 1
	s_mul_i32 s4, s10, s65
	s_mul_hi_u32 s5, s10, s88
	s_add_i32 s5, s5, s4
	s_mul_i32 s4, s10, s88
	s_add_u32 s12, s4, s2
	s_addc_u32 s13, s5, s15
	v_cmp_gt_i64_e32 vcc, s[12:13], v[148:149]
	v_cmp_lt_i64_e64 s[34:35], s[12:13], v[146:147]
	s_cbranch_vccnz .LBB0_299
	s_and_b32 s4, s12, 7
	s_lshr_b32 s5, s12, 3
	s_and_b32 s42, s5, 7
	s_lshl_b32 s4, s4, 3
	s_add_i32 s4, s4, s42
	s_lshr_b32 s40, s5, 3
	s_cmp_gt_i32 s4, 31
	s_cselect_b32 s5, 2, 1
	s_add_i32 s42, s5, s4

;     __host__ __device__ bool next(int i, Unit& u) const {
;         const long L = (long)i * G + c; if (L >= nwg) return false;
;     ...
;         int nN = this->nN, nM = this->nM, nwg = this->nwg; asm volatile("" : "+s"(nN), "+s"(nM), "+s"(nwg));
;     ...
;         int wgid = (int)L; { const int q = nwg / NXCD, r = nwg % NXCD, xcd = wgid % NXCD, off = wgid / NXCD; wgid = (xcd < r ? xcd * (q + 1) : r * (q + 1) + (xcd - r) * q) + off; }
;         const int nig = wgm * nN, gid = wgid / nig, fm = gid * wgm, gsz = (nM - fm) < wgm ? (nM - fm) : wgm;
;         u.pm = fm + ((wgid % nig) % gsz); u.pn = (wgid % nig) / gsz; u.z = 0; u.k0 = 0; u.nt = ntk;
;         if (latonly) u.pm += 1 + (u.pm >= 32 ? 1 : 0);
.LBB0_1300:
	s_add_i32 s33, s33, 1
	s_mul_i32 s4, s33, s15
	s_mul_hi_u32 s5, s33, s88
	s_add_i32 s5, s5, s4
	s_mul_i32 s4, s33, s88
	s_add_u32 s12, s4, s2
	s_addc_u32 s13, s5, s14
	v_cmp_gt_i64_e32 vcc, s[12:13], v[148:149]
	v_cmp_lt_i64_e64 s[42:43], s[12:13], v[146:147]
	s_cbranch_vccnz .LBB0_1306
	s_and_b32 s4, s12, 7
	s_lshr_b32 s5, s12, 3
	s_and_b32 s40, s5, 7
	s_lshl_b32 s4, s4, 3
	s_add_i32 s4, s4, s40
	s_lshr_b32 s38, s5, 3
	s_cmp_gt_i32 s4, 31
	s_cselect_b32 s5, 2, 1
	s_add_i32 s40, s5, s4

;     __host__ __device__ bool next(int i, Unit& u) const {
;         const long L = (long)i * G + c; if (L >= nwg) return false;
;     ...
;         int nN = this->nN, nM = this->nM, nwg = this->nwg; asm volatile("" : "+s"(nN), "+s"(nM), "+s"(nwg));
;     ...
;         int wgid = (int)L; { const int q = nwg / NXCD, r = nwg % NXCD, xcd = wgid % NXCD, off = wgid / NXCD; wgid = (xcd < r ? xcd * (q + 1) : r * (q + 1) + (xcd - r) * q) + off; }
;         const int nig = wgm * nN, gid = wgid / nig, fm = gid * wgm, gsz = (nM - fm) < wgm ? (nM - fm) : wgm;
;         u.pm = fm + ((wgid % nig) % gsz); u.pn = (wgid % nig) / gsz; u.z = 0; u.k0 = 0; u.nt = ntk;
;         if (latonly) u.pm += 1 + (u.pm >= 32 ? 1 : 0);
.LBB0_1650:
	s_add_i32 s33, s33, 1
	s_mul_i32 s4, s33, s15
	s_mul_hi_u32 s5, s33, s88
	s_add_i32 s5, s5, s4
	s_mul_i32 s4, s33, s88
	s_add_u32 s12, s4, s2
	s_addc_u32 s13, s5, s14
	v_cmp_gt_i64_e32 vcc, s[12:13], v[148:149]
	v_cmp_lt_i64_e64 s[44:45], s[12:13], v[146:147]
	s_cbranch_vccnz .LBB0_1656
	s_and_b32 s4, s12, 7
	s_lshr_b32 s5, s12, 3
	s_and_b32 s40, s5, 7
	s_lshl_b32 s4, s4, 3
	s_add_i32 s4, s4, s40
	s_lshr_b32 s38, s5, 3
	s_cmp_gt_i32 s4, 31
	s_cselect_b32 s5, 2, 1
	s_add_i32 s40, s5, s4

;     __host__ __device__ bool next(int i, Unit& u) const {
;         const long L = (long)i * G + c; if (L >= nwg) return false;
;     ...
;         int nN = this->nN, nM = this->nM, nwg = this->nwg; asm volatile("" : "+s"(nN), "+s"(nM), "+s"(nwg));
;     ...
;         int wgid = (int)L; { const int q = nwg / NXCD, r = nwg % NXCD, xcd = wgid % NXCD, off = wgid / NXCD; wgid = (xcd < r ? xcd * (q + 1) : r * (q + 1) + (xcd - r) * q) + off; }
;         const int nig = wgm * nN, gid = wgid / nig, fm = gid * wgm, gsz = (nM - fm) < wgm ? (nM - fm) : wgm;
;         u.pm = fm + ((wgid % nig) % gsz); u.pn = (wgid % nig) / gsz; u.z = 0; u.k0 = 0; u.nt = ntk;
;         if (latonly) u.pm += 1 + (u.pm >= 32 ? 1 : 0);
.LBB0_3051:
	s_add_i32 s39, s39, 1
	v_readlane_b32 s4, v254, 57
	s_mul_i32 s4, s39, s4
	s_mul_hi_u32 s5, s39, s88
	s_add_i32 s5, s5, s4
	s_mul_i32 s4, s39, s88
	s_add_u32 s12, s4, s2
	v_readlane_b32 s4, v254, 54
	s_addc_u32 s13, s5, s4
	v_cmp_gt_i64_e32 vcc, s[12:13], v[148:149]
	v_cmp_lt_i64_e64 s[36:37], s[12:13], v[146:147]
	s_cbranch_vccnz .LBB0_3057
	s_and_b32 s4, s12, 7
	s_lshr_b32 s5, s12, 3
	s_and_b32 s22, s5, 7
	s_lshl_b32 s4, s4, 3
	s_add_i32 s4, s4, s22
	s_lshr_b32 s20, s5, 3
	s_cmp_gt_i32 s4, 31
	s_cselect_b32 s5, 2, 1
	s_add_i32 s22, s5, s4
